# all five GEMM K-loops: s_setprio flips removed, static priority 1 for waves 4-7 inside the loop
# baseline (speedup 1.0000x reference)
.LBB0_501:
	s_lshl_b32 s34, s67, 8
	s_ashr_i32 s35, s34, 31
	s_lshl_b64 s[34:35], s[34:35], 11
	s_add_u32 s34, s94, s34
	s_addc_u32 s35, s95, s35
	s_and_b64 s[36:37], s[4:5], exec
	s_cselect_b32 s68, s35, s39
	s_cselect_b32 s69, s34, s38
	s_ashr_i32 s31, s30, 31
	s_lshl_b64 s[36:37], s[30:31], 19
	s_add_u32 s36, s54, s36
	s_addc_u32 s37, s55, s37
	s_and_b64 s[44:45], s[4:5], exec
	v_mov_b32_e32 v2, v0
	v_mov_b32_e32 v3, v0
	s_cselect_b32 s31, s37, s41
	s_cselect_b32 s70, s36, s40
	s_add_u32 s71, s40, 0x100
	v_mov_b32_e32 v1, v0
	v_mov_b64_e32 v[6:7], v[2:3]
	v_mov_b64_e32 v[10:11], v[2:3]
	v_mov_b64_e32 v[22:23], v[2:3]
	v_mov_b64_e32 v[26:27], v[2:3]
	v_mov_b64_e32 v[38:39], v[2:3]
	v_mov_b64_e32 v[42:43], v[2:3]
	v_mov_b64_e32 v[54:55], v[2:3]
	v_mov_b64_e32 v[58:59], v[2:3]
	v_mov_b64_e32 v[14:15], v[2:3]
	v_mov_b64_e32 v[18:19], v[2:3]
	v_mov_b64_e32 v[30:31], v[2:3]
	v_mov_b64_e32 v[34:35], v[2:3]
	v_mov_b64_e32 v[46:47], v[2:3]
	v_mov_b64_e32 v[50:51], v[2:3]
	s_waitcnt lgkmcnt(0)
	v_mov_b64_e32 v[62:63], v[2:3]
	v_mov_b64_e32 v[66:67], v[2:3]
	v_mov_b64_e32 v[70:71], v[2:3]
	v_mov_b64_e32 v[74:75], v[2:3]
	v_mov_b64_e32 v[86:87], v[2:3]
	v_mov_b64_e32 v[90:91], v[2:3]
	v_mov_b64_e32 v[102:103], v[2:3]
	v_mov_b64_e32 v[106:107], v[2:3]
	v_mov_b64_e32 v[118:119], v[2:3]
	v_mov_b64_e32 v[122:123], v[2:3]
	v_mov_b64_e32 v[78:79], v[2:3]
	v_mov_b64_e32 v[82:83], v[2:3]
	v_mov_b64_e32 v[94:95], v[2:3]
	v_mov_b64_e32 v[98:99], v[2:3]
	v_mov_b64_e32 v[110:111], v[2:3]
	v_mov_b64_e32 v[114:115], v[2:3]
	v_mov_b64_e32 v[126:127], v[2:3]
	v_mov_b64_e32 v[130:131], v[2:3]
	v_lshl_add_u32 v174, s42, 8, v180
	v_lshl_or_b32 v172, s43, 8, v182
	v_lshl_add_u64 v[176:177], s[38:39], 0, v[164:165]
	v_lshl_add_u64 v[178:179], s[38:39], 0, v[166:167]
	s_addc_u32 s72, s41, 0
	s_mov_b32 s73, -2
	s_mov_b64 s[40:41], 0
	v_mov_b64_e32 v[4:5], v[0:1]
	v_mov_b64_e32 v[8:9], v[0:1]
	v_mov_b64_e32 v[20:21], v[0:1]
	v_mov_b64_e32 v[24:25], v[0:1]
	v_mov_b64_e32 v[36:37], v[0:1]
	v_mov_b64_e32 v[40:41], v[0:1]
	v_mov_b64_e32 v[52:53], v[0:1]
	v_mov_b64_e32 v[56:57], v[0:1]
	v_mov_b64_e32 v[12:13], v[0:1]
	v_mov_b64_e32 v[16:17], v[0:1]
	v_mov_b64_e32 v[28:29], v[0:1]
	v_mov_b64_e32 v[32:33], v[0:1]
	v_mov_b64_e32 v[44:45], v[0:1]
	v_mov_b64_e32 v[48:49], v[0:1]
	v_mov_b64_e32 v[60:61], v[0:1]
	v_mov_b64_e32 v[64:65], v[0:1]
	v_mov_b64_e32 v[68:69], v[0:1]
	v_mov_b64_e32 v[72:73], v[0:1]
	v_mov_b64_e32 v[84:85], v[0:1]
	v_mov_b64_e32 v[88:89], v[0:1]
	v_mov_b64_e32 v[100:101], v[0:1]
	v_mov_b64_e32 v[104:105], v[0:1]
	v_mov_b64_e32 v[116:117], v[0:1]
	v_mov_b64_e32 v[120:121], v[0:1]
	v_mov_b64_e32 v[76:77], v[0:1]
	v_mov_b64_e32 v[80:81], v[0:1]
	v_mov_b64_e32 v[92:93], v[0:1]
	v_mov_b64_e32 v[96:97], v[0:1]
	v_mov_b64_e32 v[108:109], v[0:1]
	v_mov_b64_e32 v[112:113], v[0:1]
	v_mov_b64_e32 v[124:125], v[0:1]
	v_mov_b64_e32 v[128:129], v[0:1]
	s_setprio 0
	s_cmp_lt_u32 s46, 0x1000
	s_cbranch_scc1 .Lsprio_p4
	s_setprio 1

.LBB0_502:
	v_add_u32_e32 v1, s65, v181
	ds_read_b128 v[132:135], v1
	ds_read_b128 v[136:139], v1 offset:1024
	ds_read_b128 v[140:143], v1 offset:2048
	ds_read_b128 v[144:147], v1 offset:3072
	v_add_u32_e32 v1, s66, v181
	s_add_u32 s42, s38, s40
	ds_read_b128 v[148:151], v1
	ds_read_b128 v[152:155], v1 offset:1024
	ds_read_b128 v[184:187], v1 offset:2048
	ds_read_b128 v[188:191], v1 offset:3072
	s_addc_u32 s43, s39, s41
	s_add_u32 s42, s42, 0x100
	s_addc_u32 s43, s43, 0
	s_add_u32 s74, s71, s40
	s_addc_u32 s75, s72, s41
	s_cmpk_eq_i32 s40, 0x700
	s_cselect_b32 s45, s68, s43
	s_cselect_b32 s44, s69, s42
	s_cselect_b32 s43, s31, s75
	s_cselect_b32 s42, s70, s74
	v_lshl_add_u64 v[2:3], v[176:177], 0, s[40:41]
	s_add_i32 m0, s47, 0xc000
	ds_read_b128 v[192:195], v183
	ds_read_b128 v[196:199], v183 offset:1024
	ds_read_b128 v[200:203], v183 offset:2048
	ds_read_b128 v[204:207], v183 offset:3072
	ds_read_b128 v[210:213], v183 offset:4096
	ds_read_b128 v[214:217], v183 offset:5120
	ds_read_b128 v[218:221], v183 offset:6144
	ds_read_b128 v[222:225], v183 offset:7168
	global_load_lds_dwordx4 v[2:3], off
	v_lshl_add_u64 v[2:3], v[178:179], 0, s[40:41]
	s_add_i32 m0, s47, 0xe000
	s_nop 0
	global_load_lds_dwordx4 v[2:3], off
	s_waitcnt vmcnt(8)
	s_waitcnt lgkmcnt(0)
	s_barrier
	s_waitcnt lgkmcnt(0)
	v_mfma_f32_16x16x32_bf16 v[128:131], v[132:135], v[192:195], v[128:131]
	v_mfma_f32_16x16x32_bf16 v[124:127], v[140:143], v[192:195], v[124:127]
	v_mfma_f32_16x16x32_bf16 v[112:115], v[132:135], v[200:203], v[112:115]
	v_mfma_f32_16x16x32_bf16 v[108:111], v[140:143], v[200:203], v[108:111]
	v_mfma_f32_16x16x32_bf16 v[96:99], v[132:135], v[210:213], v[96:99]
	v_mfma_f32_16x16x32_bf16 v[92:95], v[140:143], v[210:213], v[92:95]
	v_mfma_f32_16x16x32_bf16 v[80:83], v[132:135], v[218:221], v[80:83]
	v_mfma_f32_16x16x32_bf16 v[76:79], v[140:143], v[218:221], v[76:79]
	v_mfma_f32_16x16x32_bf16 v[128:131], v[136:139], v[196:199], v[128:131]
	v_mfma_f32_16x16x32_bf16 v[124:127], v[144:147], v[196:199], v[124:127]
	v_mfma_f32_16x16x32_bf16 v[112:115], v[136:139], v[204:207], v[112:115]
	v_mfma_f32_16x16x32_bf16 v[108:111], v[144:147], v[204:207], v[108:111]
	v_mfma_f32_16x16x32_bf16 v[96:99], v[136:139], v[214:217], v[96:99]
	v_mfma_f32_16x16x32_bf16 v[92:95], v[144:147], v[214:217], v[92:95]
	v_mfma_f32_16x16x32_bf16 v[80:83], v[136:139], v[222:225], v[80:83]
	v_mfma_f32_16x16x32_bf16 v[76:79], v[144:147], v[222:225], v[76:79]
	v_mfma_f32_16x16x32_bf16 v[120:123], v[148:151], v[192:195], v[120:123]
	v_mfma_f32_16x16x32_bf16 v[116:119], v[184:187], v[192:195], v[116:119]
	v_mfma_f32_16x16x32_bf16 v[104:107], v[148:151], v[200:203], v[104:107]
	v_mfma_f32_16x16x32_bf16 v[100:103], v[184:187], v[200:203], v[100:103]
	v_mfma_f32_16x16x32_bf16 v[88:91], v[148:151], v[210:213], v[88:91]
	v_mfma_f32_16x16x32_bf16 v[84:87], v[184:187], v[210:213], v[84:87]
	v_mfma_f32_16x16x32_bf16 v[72:75], v[148:151], v[218:221], v[72:75]
	v_mfma_f32_16x16x32_bf16 v[68:71], v[184:187], v[218:221], v[68:71]
	v_mfma_f32_16x16x32_bf16 v[120:123], v[152:155], v[196:199], v[120:123]
	v_mfma_f32_16x16x32_bf16 v[116:119], v[188:191], v[196:199], v[116:119]
	v_mfma_f32_16x16x32_bf16 v[104:107], v[152:155], v[204:207], v[104:107]
	v_mfma_f32_16x16x32_bf16 v[100:103], v[188:191], v[204:207], v[100:103]
	v_mfma_f32_16x16x32_bf16 v[88:91], v[152:155], v[214:217], v[88:91]
	v_mfma_f32_16x16x32_bf16 v[84:87], v[188:191], v[214:217], v[84:87]
	v_mfma_f32_16x16x32_bf16 v[72:75], v[152:155], v[222:225], v[72:75]
	v_mfma_f32_16x16x32_bf16 v[68:71], v[188:191], v[222:225], v[68:71]
	s_barrier
	s_add_i32 s74, s65, s46
	v_lshl_add_u64 v[226:227], s[42:43], 0, v[158:159]
	s_mov_b32 m0, s74
	ds_read_b128 v[192:195], v183 offset:16384
	ds_read_b128 v[196:199], v183 offset:17408
	ds_read_b128 v[200:203], v183 offset:18432
	ds_read_b128 v[204:207], v183 offset:19456
	ds_read_b128 v[210:213], v183 offset:20480
	ds_read_b128 v[214:217], v183 offset:21504
	ds_read_b128 v[218:221], v183 offset:22528
	ds_read_b128 v[222:225], v183 offset:23552
	global_load_lds_dwordx4 v[226:227], off
	s_add_i32 m0, s74, 0x2000
	s_add_u32 s74, s42, 0x40000
	v_lshl_add_u64 v[228:229], s[42:43], 0, v[162:163]
	s_addc_u32 s75, s43, 0
	s_add_i32 s76, s66, s46
	global_load_lds_dwordx4 v[228:229], off
	v_lshl_add_u64 v[2:3], s[74:75], 0, v[158:159]
	s_mov_b32 m0, s76
	v_lshl_add_u64 v[230:231], s[44:45], 0, v[156:157]
	global_load_lds_dwordx4 v[2:3], off
	v_lshl_add_u64 v[2:3], s[74:75], 0, v[162:163]
	s_add_i32 m0, s76, 0x2000
	v_lshl_add_u64 v[232:233], s[44:45], 0, v[160:161]
	global_load_lds_dwordx4 v[2:3], off
	s_mov_b32 m0, s47
	s_nop 0
	global_load_lds_dwordx4 v[230:231], off
	s_mov_b32 m0, s48
	s_nop 0
	global_load_lds_dwordx4 v[232:233], off
	s_waitcnt vmcnt(8)
	s_waitcnt lgkmcnt(0)
	s_barrier
	s_waitcnt lgkmcnt(0)
	v_mfma_f32_16x16x32_bf16 v[64:67], v[132:135], v[192:195], v[64:67]
	v_mfma_f32_16x16x32_bf16 v[60:63], v[140:143], v[192:195], v[60:63]
	v_mfma_f32_16x16x32_bf16 v[48:51], v[132:135], v[200:203], v[48:51]
	v_mfma_f32_16x16x32_bf16 v[44:47], v[140:143], v[200:203], v[44:47]
	v_mfma_f32_16x16x32_bf16 v[32:35], v[132:135], v[210:213], v[32:35]
	v_mfma_f32_16x16x32_bf16 v[28:31], v[140:143], v[210:213], v[28:31]
	v_mfma_f32_16x16x32_bf16 v[16:19], v[132:135], v[218:221], v[16:19]
	v_mfma_f32_16x16x32_bf16 v[12:15], v[140:143], v[218:221], v[12:15]
	v_mfma_f32_16x16x32_bf16 v[64:67], v[136:139], v[196:199], v[64:67]
	v_mfma_f32_16x16x32_bf16 v[60:63], v[144:147], v[196:199], v[60:63]
	v_mfma_f32_16x16x32_bf16 v[48:51], v[136:139], v[204:207], v[48:51]
	v_mfma_f32_16x16x32_bf16 v[44:47], v[144:147], v[204:207], v[44:47]
	v_mfma_f32_16x16x32_bf16 v[32:35], v[136:139], v[214:217], v[32:35]
	v_mfma_f32_16x16x32_bf16 v[28:31], v[144:147], v[214:217], v[28:31]
	v_mfma_f32_16x16x32_bf16 v[16:19], v[136:139], v[222:225], v[16:19]
	v_mfma_f32_16x16x32_bf16 v[12:15], v[144:147], v[222:225], v[12:15]
	v_mfma_f32_16x16x32_bf16 v[56:59], v[148:151], v[192:195], v[56:59]
	v_mfma_f32_16x16x32_bf16 v[52:55], v[184:187], v[192:195], v[52:55]
	v_mfma_f32_16x16x32_bf16 v[40:43], v[148:151], v[200:203], v[40:43]
	v_mfma_f32_16x16x32_bf16 v[36:39], v[184:187], v[200:203], v[36:39]
	v_mfma_f32_16x16x32_bf16 v[24:27], v[148:151], v[210:213], v[24:27]
	v_mfma_f32_16x16x32_bf16 v[20:23], v[184:187], v[210:213], v[20:23]
	v_mfma_f32_16x16x32_bf16 v[8:11], v[148:151], v[218:221], v[8:11]
	v_mfma_f32_16x16x32_bf16 v[2:5], v[184:187], v[218:221], v[4:7]
	v_mfma_f32_16x16x32_bf16 v[56:59], v[152:155], v[196:199], v[56:59]
	v_mfma_f32_16x16x32_bf16 v[52:55], v[188:191], v[196:199], v[52:55]
	v_mfma_f32_16x16x32_bf16 v[40:43], v[152:155], v[204:207], v[40:43]
	v_mfma_f32_16x16x32_bf16 v[36:39], v[188:191], v[204:207], v[36:39]
	v_mfma_f32_16x16x32_bf16 v[24:27], v[152:155], v[214:217], v[24:27]
	v_mfma_f32_16x16x32_bf16 v[20:23], v[188:191], v[214:217], v[20:23]
	v_mfma_f32_16x16x32_bf16 v[8:11], v[152:155], v[222:225], v[8:11]
	v_mfma_f32_16x16x32_bf16 v[2:5], v[188:191], v[222:225], v[2:5]
	s_barrier
	s_add_i32 s74, 0, 0x18000
	v_add_u32_e32 v1, s74, v181
	s_add_i32 s75, 0, 0x1c000
	ds_read_b128 v[132:135], v1
	ds_read_b128 v[136:139], v1 offset:1024
	ds_read_b128 v[140:143], v1 offset:2048
	ds_read_b128 v[144:147], v1 offset:3072
	v_add_u32_e32 v1, s75, v181
	ds_read_b128 v[148:151], v1
	ds_read_b128 v[152:155], v1 offset:1024
	ds_read_b128 v[184:187], v1 offset:2048
	ds_read_b128 v[188:191], v1 offset:3072
	s_add_u32 s44, s44, 0x40000
	s_addc_u32 s45, s45, 0
	s_mov_b32 m0, s49
	v_lshl_add_u64 v[6:7], s[44:45], 0, v[156:157]
	ds_read_b128 v[192:195], v183 offset:32768
	ds_read_b128 v[196:199], v183 offset:33792
	ds_read_b128 v[200:203], v183 offset:34816
	ds_read_b128 v[204:207], v183 offset:35840
	ds_read_b128 v[210:213], v183 offset:36864
	ds_read_b128 v[214:217], v183 offset:37888
	ds_read_b128 v[218:221], v183 offset:38912
	ds_read_b128 v[222:225], v183 offset:39936
	global_load_lds_dwordx4 v[6:7], off
	v_lshl_add_u64 v[6:7], s[44:45], 0, v[160:161]
	s_mov_b32 m0, s50
	s_nop 0
	global_load_lds_dwordx4 v[6:7], off
	s_waitcnt vmcnt(8)
	s_waitcnt lgkmcnt(0)
	s_barrier
	s_waitcnt lgkmcnt(0)
	v_mfma_f32_16x16x32_bf16 v[128:131], v[132:135], v[192:195], v[128:131]
	v_mfma_f32_16x16x32_bf16 v[124:127], v[140:143], v[192:195], v[124:127]
	v_mfma_f32_16x16x32_bf16 v[112:115], v[132:135], v[200:203], v[112:115]
	v_mfma_f32_16x16x32_bf16 v[108:111], v[140:143], v[200:203], v[108:111]
	v_mfma_f32_16x16x32_bf16 v[96:99], v[132:135], v[210:213], v[96:99]
	v_mfma_f32_16x16x32_bf16 v[92:95], v[140:143], v[210:213], v[92:95]
	v_mfma_f32_16x16x32_bf16 v[80:83], v[132:135], v[218:221], v[80:83]
	v_mfma_f32_16x16x32_bf16 v[76:79], v[140:143], v[218:221], v[76:79]
	v_mfma_f32_16x16x32_bf16 v[128:131], v[136:139], v[196:199], v[128:131]
	v_mfma_f32_16x16x32_bf16 v[124:127], v[144:147], v[196:199], v[124:127]
	v_mfma_f32_16x16x32_bf16 v[112:115], v[136:139], v[204:207], v[112:115]
	v_mfma_f32_16x16x32_bf16 v[108:111], v[144:147], v[204:207], v[108:111]
	v_mfma_f32_16x16x32_bf16 v[96:99], v[136:139], v[214:217], v[96:99]
	v_mfma_f32_16x16x32_bf16 v[92:95], v[144:147], v[214:217], v[92:95]
	v_mfma_f32_16x16x32_bf16 v[80:83], v[136:139], v[222:225], v[80:83]
	v_mfma_f32_16x16x32_bf16 v[76:79], v[144:147], v[222:225], v[76:79]
	v_mfma_f32_16x16x32_bf16 v[120:123], v[148:151], v[192:195], v[120:123]
	v_mfma_f32_16x16x32_bf16 v[116:119], v[184:187], v[192:195], v[116:119]
	v_mfma_f32_16x16x32_bf16 v[104:107], v[148:151], v[200:203], v[104:107]
	v_mfma_f32_16x16x32_bf16 v[100:103], v[184:187], v[200:203], v[100:103]
	v_mfma_f32_16x16x32_bf16 v[88:91], v[148:151], v[210:213], v[88:91]
	v_mfma_f32_16x16x32_bf16 v[84:87], v[184:187], v[210:213], v[84:87]
	v_mfma_f32_16x16x32_bf16 v[72:75], v[148:151], v[218:221], v[72:75]
	v_mfma_f32_16x16x32_bf16 v[68:71], v[184:187], v[218:221], v[68:71]
	v_mfma_f32_16x16x32_bf16 v[120:123], v[152:155], v[196:199], v[120:123]
	v_mfma_f32_16x16x32_bf16 v[116:119], v[188:191], v[196:199], v[116:119]
	v_mfma_f32_16x16x32_bf16 v[104:107], v[152:155], v[204:207], v[104:107]
	v_mfma_f32_16x16x32_bf16 v[100:103], v[188:191], v[204:207], v[100:103]
	v_mfma_f32_16x16x32_bf16 v[88:91], v[152:155], v[214:217], v[88:91]
	v_mfma_f32_16x16x32_bf16 v[84:87], v[188:191], v[214:217], v[84:87]
	v_mfma_f32_16x16x32_bf16 v[72:75], v[152:155], v[222:225], v[72:75]
	v_mfma_f32_16x16x32_bf16 v[68:71], v[188:191], v[222:225], v[68:71]
	s_barrier
	s_add_i32 s44, s74, s46
	v_lshl_add_u64 v[6:7], v[226:227], 0, s[14:15]
	s_mov_b32 m0, s44
	ds_read_b128 v[192:195], v183 offset:49152
	ds_read_b128 v[196:199], v183 offset:50176
	ds_read_b128 v[200:203], v183 offset:51200
	ds_read_b128 v[204:207], v183 offset:52224
	ds_read_b128 v[210:213], v183 offset:53248
	ds_read_b128 v[214:217], v183 offset:54272
	ds_read_b128 v[218:221], v183 offset:55296
	ds_read_b128 v[222:225], v183 offset:56320
	global_load_lds_dwordx4 v[6:7], off
	s_add_i32 m0, s44, 0x2000
	s_add_u32 s42, s42, 0x40080
	v_lshl_add_u64 v[6:7], v[228:229], 0, s[14:15]
	s_addc_u32 s43, s43, 0
	s_add_i32 s44, s75, s46
	global_load_lds_dwordx4 v[6:7], off
	v_lshl_add_u64 v[6:7], s[42:43], 0, v[158:159]
	s_mov_b32 m0, s44
	s_nop 0
	global_load_lds_dwordx4 v[6:7], off
	v_lshl_add_u64 v[6:7], s[42:43], 0, v[162:163]
	s_add_i32 m0, s44, 0x2000
	s_nop 0
	global_load_lds_dwordx4 v[6:7], off
	v_lshl_add_u64 v[6:7], v[230:231], 0, s[14:15]
	s_mov_b32 m0, s62
	s_nop 0
	global_load_lds_dwordx4 v[6:7], off
	v_lshl_add_u64 v[6:7], v[232:233], 0, s[14:15]
	s_mov_b32 m0, s63
	s_nop 0
	global_load_lds_dwordx4 v[6:7], off
	s_waitcnt vmcnt(8)
	s_waitcnt lgkmcnt(0)
	s_barrier
	s_waitcnt lgkmcnt(0)
	v_mfma_f32_16x16x32_bf16 v[64:67], v[132:135], v[192:195], v[64:67]
	v_mfma_f32_16x16x32_bf16 v[60:63], v[140:143], v[192:195], v[60:63]
	v_mfma_f32_16x16x32_bf16 v[48:51], v[132:135], v[200:203], v[48:51]
	v_mfma_f32_16x16x32_bf16 v[44:47], v[140:143], v[200:203], v[44:47]
	v_mfma_f32_16x16x32_bf16 v[32:35], v[132:135], v[210:213], v[32:35]
	v_mfma_f32_16x16x32_bf16 v[28:31], v[140:143], v[210:213], v[28:31]
	v_mfma_f32_16x16x32_bf16 v[16:19], v[132:135], v[218:221], v[16:19]
	v_mfma_f32_16x16x32_bf16 v[12:15], v[140:143], v[218:221], v[12:15]
	v_mfma_f32_16x16x32_bf16 v[64:67], v[136:139], v[196:199], v[64:67]
	v_mfma_f32_16x16x32_bf16 v[60:63], v[144:147], v[196:199], v[60:63]
	v_mfma_f32_16x16x32_bf16 v[48:51], v[136:139], v[204:207], v[48:51]
	v_mfma_f32_16x16x32_bf16 v[44:47], v[144:147], v[204:207], v[44:47]
	v_mfma_f32_16x16x32_bf16 v[32:35], v[136:139], v[214:217], v[32:35]
	v_mfma_f32_16x16x32_bf16 v[28:31], v[144:147], v[214:217], v[28:31]
	v_mfma_f32_16x16x32_bf16 v[16:19], v[136:139], v[222:225], v[16:19]
	v_mfma_f32_16x16x32_bf16 v[12:15], v[144:147], v[222:225], v[12:15]
	v_mfma_f32_16x16x32_bf16 v[56:59], v[148:151], v[192:195], v[56:59]
	v_mfma_f32_16x16x32_bf16 v[52:55], v[184:187], v[192:195], v[52:55]
	v_mfma_f32_16x16x32_bf16 v[40:43], v[148:151], v[200:203], v[40:43]
	v_mfma_f32_16x16x32_bf16 v[36:39], v[184:187], v[200:203], v[36:39]
	v_mfma_f32_16x16x32_bf16 v[24:27], v[148:151], v[210:213], v[24:27]
	v_mfma_f32_16x16x32_bf16 v[20:23], v[184:187], v[210:213], v[20:23]
	v_mfma_f32_16x16x32_bf16 v[6:9], v[148:151], v[218:221], v[8:11]
	v_mfma_f32_16x16x32_bf16 v[2:5], v[184:187], v[218:221], v[2:5]
	v_mfma_f32_16x16x32_bf16 v[56:59], v[152:155], v[196:199], v[56:59]
	v_mfma_f32_16x16x32_bf16 v[52:55], v[188:191], v[196:199], v[52:55]
	v_mfma_f32_16x16x32_bf16 v[40:43], v[152:155], v[204:207], v[40:43]
	v_mfma_f32_16x16x32_bf16 v[36:39], v[188:191], v[204:207], v[36:39]
	v_mfma_f32_16x16x32_bf16 v[24:27], v[152:155], v[214:217], v[24:27]
	v_mfma_f32_16x16x32_bf16 v[20:23], v[188:191], v[214:217], v[20:23]
	v_mfma_f32_16x16x32_bf16 v[8:11], v[152:155], v[222:225], v[6:9]
	v_mfma_f32_16x16x32_bf16 v[4:7], v[188:191], v[222:225], v[2:5]
	s_barrier
	s_add_i32 s73, s73, 2
	s_add_u32 s40, s40, 0x100
	s_addc_u32 s41, s41, 0
	s_cmp_gt_u32 s73, 13
	s_cbranch_scc1 .LBB0_505

.LBB0_505:
	s_setprio 0
	s_and_b64 vcc, exec, s[16:17]
	s_cbranch_vccz .LBB0_507
	s_barrier

.LBB0_805:
	s_add_u32 s26, s26, 0xb0080
	s_addc_u32 s27, s27, 0
	s_add_u32 s53, s28, 0x100
	v_mov_b32_e32 v0, 0
	s_addc_u32 s54, s29, 0
	s_mov_b32 s55, -2
	v_mov_b32_e32 v1, v0
	v_mov_b32_e32 v2, v0
	v_mov_b32_e32 v3, v0
	v_mov_b32_e32 v4, v0
	v_mov_b32_e32 v5, v0
	v_mov_b32_e32 v6, v0
	v_mov_b32_e32 v7, v0
	v_mov_b32_e32 v16, v0
	v_mov_b32_e32 v17, v0
	v_mov_b32_e32 v18, v0
	v_mov_b32_e32 v19, v0
	v_mov_b32_e32 v20, v0
	v_mov_b32_e32 v21, v0
	v_mov_b32_e32 v22, v0
	v_mov_b32_e32 v23, v0
	v_mov_b32_e32 v32, v0
	v_mov_b32_e32 v33, v0
	v_mov_b32_e32 v34, v0
	v_mov_b32_e32 v35, v0
	v_mov_b32_e32 v36, v0
	v_mov_b32_e32 v37, v0
	v_mov_b32_e32 v38, v0
	v_mov_b32_e32 v39, v0
	v_mov_b32_e32 v48, v0
	v_mov_b32_e32 v49, v0
	v_mov_b32_e32 v50, v0
	v_mov_b32_e32 v51, v0
	v_mov_b32_e32 v52, v0
	v_mov_b32_e32 v53, v0
	v_mov_b32_e32 v54, v0
	v_mov_b32_e32 v55, v0
	v_mov_b32_e32 v8, v0
	v_mov_b32_e32 v9, v0
	v_mov_b32_e32 v10, v0
	v_mov_b32_e32 v11, v0
	v_mov_b32_e32 v12, v0
	v_mov_b32_e32 v13, v0
	v_mov_b32_e32 v14, v0
	v_mov_b32_e32 v15, v0
	v_mov_b32_e32 v24, v0
	v_mov_b32_e32 v25, v0
	v_mov_b32_e32 v26, v0
	v_mov_b32_e32 v27, v0
	v_mov_b32_e32 v28, v0
	v_mov_b32_e32 v29, v0
	v_mov_b32_e32 v30, v0
	v_mov_b32_e32 v31, v0
	v_mov_b32_e32 v40, v0
	v_mov_b32_e32 v41, v0
	v_mov_b32_e32 v42, v0
	v_mov_b32_e32 v43, v0
	v_mov_b32_e32 v44, v0
	v_mov_b32_e32 v45, v0
	v_mov_b32_e32 v46, v0
	v_mov_b32_e32 v47, v0
	v_mov_b32_e32 v56, v0
	v_mov_b32_e32 v57, v0
	v_mov_b32_e32 v58, v0
	v_mov_b32_e32 v59, v0
	v_mov_b32_e32 v60, v0
	v_mov_b32_e32 v61, v0
	v_mov_b32_e32 v62, v0
	v_mov_b32_e32 v63, v0
	v_mov_b32_e32 v64, v0
	v_mov_b32_e32 v65, v0
	v_mov_b32_e32 v66, v0
	v_mov_b32_e32 v67, v0
	v_mov_b32_e32 v68, v0
	v_mov_b32_e32 v69, v0
	v_mov_b32_e32 v70, v0
	v_mov_b32_e32 v71, v0
	v_mov_b32_e32 v80, v0
	v_mov_b32_e32 v81, v0
	v_mov_b32_e32 v82, v0
	v_mov_b32_e32 v83, v0
	v_mov_b32_e32 v84, v0
	v_mov_b32_e32 v85, v0
	v_mov_b32_e32 v86, v0
	v_mov_b32_e32 v87, v0
	v_mov_b32_e32 v96, v0
	v_mov_b32_e32 v97, v0
	v_mov_b32_e32 v98, v0
	v_mov_b32_e32 v99, v0
	v_mov_b32_e32 v100, v0
	v_mov_b32_e32 v101, v0
	v_mov_b32_e32 v102, v0
	v_mov_b32_e32 v103, v0
	v_mov_b32_e32 v112, v0
	v_mov_b32_e32 v113, v0
	v_mov_b32_e32 v114, v0
	v_mov_b32_e32 v115, v0
	v_mov_b32_e32 v116, v0
	v_mov_b32_e32 v117, v0
	v_mov_b32_e32 v118, v0
	v_mov_b32_e32 v119, v0
	v_mov_b32_e32 v72, v0
	v_mov_b32_e32 v73, v0
	v_mov_b32_e32 v74, v0
	v_mov_b32_e32 v75, v0
	v_mov_b32_e32 v76, v0
	v_mov_b32_e32 v77, v0
	v_mov_b32_e32 v78, v0
	v_mov_b32_e32 v79, v0
	v_mov_b32_e32 v88, v0
	v_mov_b32_e32 v89, v0
	v_mov_b32_e32 v90, v0
	v_mov_b32_e32 v91, v0
	v_mov_b32_e32 v92, v0
	v_mov_b32_e32 v93, v0
	v_mov_b32_e32 v94, v0
	v_mov_b32_e32 v95, v0
	v_mov_b32_e32 v104, v0
	v_mov_b32_e32 v105, v0
	v_mov_b32_e32 v106, v0
	v_mov_b32_e32 v107, v0
	v_mov_b32_e32 v108, v0
	v_mov_b32_e32 v109, v0
	v_mov_b32_e32 v110, v0
	v_mov_b32_e32 v111, v0
	v_mov_b32_e32 v120, v0
	v_mov_b32_e32 v121, v0
	v_mov_b32_e32 v122, v0
	v_mov_b32_e32 v123, v0
	v_mov_b32_e32 v124, v0
	v_mov_b32_e32 v125, v0
	v_mov_b32_e32 v126, v0
	v_mov_b32_e32 v127, v0
	s_setprio 0
	s_cmp_lt_u32 s36, 0x1000
	s_cbranch_scc1 .Lsprio_p11
	s_setprio 1
.Lsprio_p11:
.LBB0_806:
	ds_read_b128 v[144:147], v161
	ds_read_b128 v[148:151], v161 offset:1024
	ds_read_b128 v[152:155], v161 offset:2048
	ds_read_b128 v[164:167], v161 offset:3072
	ds_read_b128 v[168:171], v162
	ds_read_b128 v[172:175], v162 offset:1024
	ds_read_b128 v[176:179], v162 offset:2048
	ds_read_b128 v[180:183], v162 offset:3072
	s_add_u32 s28, s26, 0xfff50080
	s_addc_u32 s29, s27, -1
	s_cmp_eq_u32 s55, 40
	s_cselect_b32 s35, s5, s29
	s_cselect_b32 s34, s4, s28
	s_cselect_b32 s29, s25, s54
	s_cselect_b32 s28, s24, s53
	v_lshl_add_u64 v[156:157], s[26:27], 0, v[136:137]
	s_add_i32 m0, s37, 0xc000
	ds_read_b128 v[184:187], v163
	ds_read_b128 v[188:191], v163 offset:1024
	ds_read_b128 v[192:195], v163 offset:2048
	ds_read_b128 v[196:199], v163 offset:3072
	ds_read_b128 v[200:203], v163 offset:4096
	ds_read_b128 v[204:207], v163 offset:5120
	ds_read_b128 v[208:211], v163 offset:6144
	ds_read_b128 v[212:215], v163 offset:7168
	global_load_lds_dwordx4 v[156:157], off
	v_lshl_add_u64 v[156:157], s[26:27], 0, v[138:139]
	s_add_i32 m0, s37, 0xe000
	s_nop 0
	global_load_lds_dwordx4 v[156:157], off
	s_waitcnt vmcnt(8)
	s_waitcnt lgkmcnt(0)
	s_barrier
	s_waitcnt lgkmcnt(0)
	v_mfma_f32_16x16x32_bf16 v[124:127], v[144:147], v[184:187], v[124:127]
	v_mfma_f32_16x16x32_bf16 v[120:123], v[152:155], v[184:187], v[120:123]
	v_mfma_f32_16x16x32_bf16 v[108:111], v[144:147], v[192:195], v[108:111]
	v_mfma_f32_16x16x32_bf16 v[104:107], v[152:155], v[192:195], v[104:107]
	v_mfma_f32_16x16x32_bf16 v[92:95], v[144:147], v[200:203], v[92:95]
	v_mfma_f32_16x16x32_bf16 v[88:91], v[152:155], v[200:203], v[88:91]
	v_mfma_f32_16x16x32_bf16 v[76:79], v[144:147], v[208:211], v[76:79]
	v_mfma_f32_16x16x32_bf16 v[72:75], v[152:155], v[208:211], v[72:75]
	v_mfma_f32_16x16x32_bf16 v[124:127], v[148:151], v[188:191], v[124:127]
	v_mfma_f32_16x16x32_bf16 v[120:123], v[164:167], v[188:191], v[120:123]
	v_mfma_f32_16x16x32_bf16 v[108:111], v[148:151], v[196:199], v[108:111]
	v_mfma_f32_16x16x32_bf16 v[104:107], v[164:167], v[196:199], v[104:107]
	v_mfma_f32_16x16x32_bf16 v[92:95], v[148:151], v[204:207], v[92:95]
	v_mfma_f32_16x16x32_bf16 v[88:91], v[164:167], v[204:207], v[88:91]
	v_mfma_f32_16x16x32_bf16 v[76:79], v[148:151], v[212:215], v[76:79]
	v_mfma_f32_16x16x32_bf16 v[72:75], v[164:167], v[212:215], v[72:75]
	v_mfma_f32_16x16x32_bf16 v[116:119], v[168:171], v[184:187], v[116:119]
	v_mfma_f32_16x16x32_bf16 v[112:115], v[176:179], v[184:187], v[112:115]
	v_mfma_f32_16x16x32_bf16 v[100:103], v[168:171], v[192:195], v[100:103]
	v_mfma_f32_16x16x32_bf16 v[96:99], v[176:179], v[192:195], v[96:99]
	v_mfma_f32_16x16x32_bf16 v[84:87], v[168:171], v[200:203], v[84:87]
	v_mfma_f32_16x16x32_bf16 v[80:83], v[176:179], v[200:203], v[80:83]
	v_mfma_f32_16x16x32_bf16 v[68:71], v[168:171], v[208:211], v[68:71]
	v_mfma_f32_16x16x32_bf16 v[64:67], v[176:179], v[208:211], v[64:67]
	v_mfma_f32_16x16x32_bf16 v[116:119], v[172:175], v[188:191], v[116:119]
	v_mfma_f32_16x16x32_bf16 v[112:115], v[180:183], v[188:191], v[112:115]
	v_mfma_f32_16x16x32_bf16 v[100:103], v[172:175], v[196:199], v[100:103]
	v_mfma_f32_16x16x32_bf16 v[96:99], v[180:183], v[196:199], v[96:99]
	v_mfma_f32_16x16x32_bf16 v[84:87], v[172:175], v[204:207], v[84:87]
	v_mfma_f32_16x16x32_bf16 v[80:83], v[180:183], v[204:207], v[80:83]
	v_mfma_f32_16x16x32_bf16 v[68:71], v[172:175], v[212:215], v[68:71]
	v_mfma_f32_16x16x32_bf16 v[64:67], v[180:183], v[212:215], v[64:67]
	s_barrier
	s_add_i32 s56, s47, s36
	v_lshl_add_u64 v[156:157], s[28:29], 0, v[130:131]
	s_mov_b32 m0, s56
	ds_read_b128 v[184:187], v163 offset:16384
	ds_read_b128 v[188:191], v163 offset:17408
	ds_read_b128 v[192:195], v163 offset:18432
	ds_read_b128 v[196:199], v163 offset:19456
	ds_read_b128 v[200:203], v163 offset:20480
	ds_read_b128 v[204:207], v163 offset:21504
	ds_read_b128 v[208:211], v163 offset:22528
	ds_read_b128 v[212:215], v163 offset:23552
	global_load_lds_dwordx4 v[156:157], off
	s_add_i32 m0, s56, 0x2000
	s_add_u32 s56, s28, 0xb0000
	v_lshl_add_u64 v[216:217], s[28:29], 0, v[134:135]
	s_addc_u32 s57, s29, 0
	s_add_i32 s58, s48, s36
	global_load_lds_dwordx4 v[216:217], off
	v_lshl_add_u64 v[218:219], s[56:57], 0, v[130:131]
	s_mov_b32 m0, s58
	v_lshl_add_u64 v[220:221], s[34:35], 0, v[132:133]
	global_load_lds_dwordx4 v[218:219], off
	v_lshl_add_u64 v[218:219], s[56:57], 0, v[134:135]
	s_add_i32 m0, s58, 0x2000
	s_nop 0
	global_load_lds_dwordx4 v[218:219], off
	v_lshl_add_u64 v[218:219], s[34:35], 0, v[128:129]
	s_mov_b32 m0, s37
	s_nop 0
	global_load_lds_dwordx4 v[218:219], off
	s_mov_b32 m0, s38
	s_nop 0
	global_load_lds_dwordx4 v[220:221], off
	s_waitcnt vmcnt(8)
	s_waitcnt lgkmcnt(0)
	s_barrier
	s_waitcnt lgkmcnt(0)
	v_mfma_f32_16x16x32_bf16 v[60:63], v[144:147], v[184:187], v[60:63]
	v_mfma_f32_16x16x32_bf16 v[56:59], v[152:155], v[184:187], v[56:59]
	v_mfma_f32_16x16x32_bf16 v[44:47], v[144:147], v[192:195], v[44:47]
	v_mfma_f32_16x16x32_bf16 v[40:43], v[152:155], v[192:195], v[40:43]
	v_mfma_f32_16x16x32_bf16 v[28:31], v[144:147], v[200:203], v[28:31]
	v_mfma_f32_16x16x32_bf16 v[24:27], v[152:155], v[200:203], v[24:27]
	v_mfma_f32_16x16x32_bf16 v[12:15], v[144:147], v[208:211], v[12:15]
	v_mfma_f32_16x16x32_bf16 v[8:11], v[152:155], v[208:211], v[8:11]
	v_mfma_f32_16x16x32_bf16 v[60:63], v[148:151], v[188:191], v[60:63]
	v_mfma_f32_16x16x32_bf16 v[56:59], v[164:167], v[188:191], v[56:59]
	v_mfma_f32_16x16x32_bf16 v[44:47], v[148:151], v[196:199], v[44:47]
	v_mfma_f32_16x16x32_bf16 v[40:43], v[164:167], v[196:199], v[40:43]
	v_mfma_f32_16x16x32_bf16 v[28:31], v[148:151], v[204:207], v[28:31]
	v_mfma_f32_16x16x32_bf16 v[24:27], v[164:167], v[204:207], v[24:27]
	v_mfma_f32_16x16x32_bf16 v[12:15], v[148:151], v[212:215], v[12:15]
	v_mfma_f32_16x16x32_bf16 v[8:11], v[164:167], v[212:215], v[8:11]
	v_mfma_f32_16x16x32_bf16 v[52:55], v[168:171], v[184:187], v[52:55]
	v_mfma_f32_16x16x32_bf16 v[48:51], v[176:179], v[184:187], v[48:51]
	v_mfma_f32_16x16x32_bf16 v[36:39], v[168:171], v[192:195], v[36:39]
	v_mfma_f32_16x16x32_bf16 v[32:35], v[176:179], v[192:195], v[32:35]
	v_mfma_f32_16x16x32_bf16 v[20:23], v[168:171], v[200:203], v[20:23]
	v_mfma_f32_16x16x32_bf16 v[16:19], v[176:179], v[200:203], v[16:19]
	v_mfma_f32_16x16x32_bf16 v[4:7], v[168:171], v[208:211], v[4:7]
	v_mfma_f32_16x16x32_bf16 v[0:3], v[176:179], v[208:211], v[0:3]
	v_mfma_f32_16x16x32_bf16 v[52:55], v[172:175], v[188:191], v[52:55]
	v_mfma_f32_16x16x32_bf16 v[48:51], v[180:183], v[188:191], v[48:51]
	v_mfma_f32_16x16x32_bf16 v[36:39], v[172:175], v[196:199], v[36:39]
	v_mfma_f32_16x16x32_bf16 v[32:35], v[180:183], v[196:199], v[32:35]
	v_mfma_f32_16x16x32_bf16 v[20:23], v[172:175], v[204:207], v[20:23]
	v_mfma_f32_16x16x32_bf16 v[16:19], v[180:183], v[204:207], v[16:19]
	v_mfma_f32_16x16x32_bf16 v[4:7], v[172:175], v[212:215], v[4:7]
	v_mfma_f32_16x16x32_bf16 v[0:3], v[180:183], v[212:215], v[0:3]
	s_barrier
	s_add_i32 s56, 0, 0x18000
	s_add_i32 s57, 0, 0x1c000
	v_add_u32_e32 v164, s56, v159
	v_add_u32_e32 v180, s57, v159
	ds_read_b128 v[144:147], v164
	ds_read_b128 v[148:151], v164 offset:1024
	ds_read_b128 v[152:155], v164 offset:2048
	ds_read_b128 v[164:167], v164 offset:3072
	ds_read_b128 v[168:171], v180
	ds_read_b128 v[172:175], v180 offset:1024
	ds_read_b128 v[176:179], v180 offset:2048
	ds_read_b128 v[180:183], v180 offset:3072
	s_add_u32 s34, s34, 0xb0000
	s_addc_u32 s35, s35, 0
	s_mov_b32 m0, s39
	v_lshl_add_u64 v[222:223], s[34:35], 0, v[128:129]
	ds_read_b128 v[184:187], v163 offset:32768
	ds_read_b128 v[188:191], v163 offset:33792
	ds_read_b128 v[192:195], v163 offset:34816
	ds_read_b128 v[196:199], v163 offset:35840
	ds_read_b128 v[200:203], v163 offset:36864
	ds_read_b128 v[204:207], v163 offset:37888
	ds_read_b128 v[208:211], v163 offset:38912
	ds_read_b128 v[212:215], v163 offset:39936
	global_load_lds_dwordx4 v[222:223], off
	v_lshl_add_u64 v[222:223], s[34:35], 0, v[132:133]
	s_mov_b32 m0, s40
	s_nop 0
	global_load_lds_dwordx4 v[222:223], off
	s_waitcnt vmcnt(8)
	s_waitcnt lgkmcnt(0)
	s_barrier
	s_waitcnt lgkmcnt(0)
	v_mfma_f32_16x16x32_bf16 v[124:127], v[144:147], v[184:187], v[124:127]
	v_mfma_f32_16x16x32_bf16 v[120:123], v[152:155], v[184:187], v[120:123]
	v_mfma_f32_16x16x32_bf16 v[108:111], v[144:147], v[192:195], v[108:111]
	v_mfma_f32_16x16x32_bf16 v[104:107], v[152:155], v[192:195], v[104:107]
	v_mfma_f32_16x16x32_bf16 v[92:95], v[144:147], v[200:203], v[92:95]
	v_mfma_f32_16x16x32_bf16 v[88:91], v[152:155], v[200:203], v[88:91]
	v_mfma_f32_16x16x32_bf16 v[76:79], v[144:147], v[208:211], v[76:79]
	v_mfma_f32_16x16x32_bf16 v[72:75], v[152:155], v[208:211], v[72:75]
	v_mfma_f32_16x16x32_bf16 v[124:127], v[148:151], v[188:191], v[124:127]
	v_mfma_f32_16x16x32_bf16 v[120:123], v[164:167], v[188:191], v[120:123]
	v_mfma_f32_16x16x32_bf16 v[108:111], v[148:151], v[196:199], v[108:111]
	v_mfma_f32_16x16x32_bf16 v[104:107], v[164:167], v[196:199], v[104:107]
	v_mfma_f32_16x16x32_bf16 v[92:95], v[148:151], v[204:207], v[92:95]
	v_mfma_f32_16x16x32_bf16 v[88:91], v[164:167], v[204:207], v[88:91]
	v_mfma_f32_16x16x32_bf16 v[76:79], v[148:151], v[212:215], v[76:79]
	v_mfma_f32_16x16x32_bf16 v[72:75], v[164:167], v[212:215], v[72:75]
	v_mfma_f32_16x16x32_bf16 v[116:119], v[168:171], v[184:187], v[116:119]
	v_mfma_f32_16x16x32_bf16 v[112:115], v[176:179], v[184:187], v[112:115]
	v_mfma_f32_16x16x32_bf16 v[100:103], v[168:171], v[192:195], v[100:103]
	v_mfma_f32_16x16x32_bf16 v[96:99], v[176:179], v[192:195], v[96:99]
	v_mfma_f32_16x16x32_bf16 v[84:87], v[168:171], v[200:203], v[84:87]
	v_mfma_f32_16x16x32_bf16 v[80:83], v[176:179], v[200:203], v[80:83]
	v_mfma_f32_16x16x32_bf16 v[68:71], v[168:171], v[208:211], v[68:71]
	v_mfma_f32_16x16x32_bf16 v[64:67], v[176:179], v[208:211], v[64:67]
	v_mfma_f32_16x16x32_bf16 v[116:119], v[172:175], v[188:191], v[116:119]
	v_mfma_f32_16x16x32_bf16 v[112:115], v[180:183], v[188:191], v[112:115]
	v_mfma_f32_16x16x32_bf16 v[100:103], v[172:175], v[196:199], v[100:103]
	v_mfma_f32_16x16x32_bf16 v[96:99], v[180:183], v[196:199], v[96:99]
	v_mfma_f32_16x16x32_bf16 v[84:87], v[172:175], v[204:207], v[84:87]
	v_mfma_f32_16x16x32_bf16 v[80:83], v[180:183], v[204:207], v[80:83]
	v_mfma_f32_16x16x32_bf16 v[68:71], v[172:175], v[212:215], v[68:71]
	v_mfma_f32_16x16x32_bf16 v[64:67], v[180:183], v[212:215], v[64:67]
	s_barrier
	s_add_i32 s34, s56, s36
	v_lshl_add_u64 v[156:157], v[156:157], 0, s[10:11]
	s_mov_b32 m0, s34
	ds_read_b128 v[184:187], v163 offset:49152
	ds_read_b128 v[188:191], v163 offset:50176
	ds_read_b128 v[192:195], v163 offset:51200
	ds_read_b128 v[196:199], v163 offset:52224
	ds_read_b128 v[200:203], v163 offset:53248
	ds_read_b128 v[204:207], v163 offset:54272
	ds_read_b128 v[208:211], v163 offset:55296
	ds_read_b128 v[212:215], v163 offset:56320
	global_load_lds_dwordx4 v[156:157], off
	s_add_i32 m0, s34, 0x2000
	s_add_u32 s28, s28, 0xb0080
	v_lshl_add_u64 v[156:157], v[216:217], 0, s[10:11]
	s_addc_u32 s29, s29, 0
	s_add_i32 s34, s57, s36
	global_load_lds_dwordx4 v[156:157], off
	v_lshl_add_u64 v[156:157], s[28:29], 0, v[130:131]
	s_mov_b32 m0, s34
	s_nop 0
	global_load_lds_dwordx4 v[156:157], off
	v_lshl_add_u64 v[156:157], s[28:29], 0, v[134:135]
	s_add_i32 m0, s34, 0x2000
	s_nop 0
	global_load_lds_dwordx4 v[156:157], off
	v_lshl_add_u64 v[156:157], v[218:219], 0, s[10:11]
	s_mov_b32 m0, s44
	s_nop 0
	global_load_lds_dwordx4 v[156:157], off
	v_lshl_add_u64 v[156:157], v[220:221], 0, s[10:11]
	s_mov_b32 m0, s45
	s_nop 0
	global_load_lds_dwordx4 v[156:157], off
	s_waitcnt vmcnt(8)
	s_waitcnt lgkmcnt(0)
	s_barrier
	s_waitcnt lgkmcnt(0)
	v_mfma_f32_16x16x32_bf16 v[60:63], v[144:147], v[184:187], v[60:63]
	v_mfma_f32_16x16x32_bf16 v[56:59], v[152:155], v[184:187], v[56:59]
	v_mfma_f32_16x16x32_bf16 v[44:47], v[144:147], v[192:195], v[44:47]
	v_mfma_f32_16x16x32_bf16 v[40:43], v[152:155], v[192:195], v[40:43]
	v_mfma_f32_16x16x32_bf16 v[28:31], v[144:147], v[200:203], v[28:31]
	v_mfma_f32_16x16x32_bf16 v[24:27], v[152:155], v[200:203], v[24:27]
	v_mfma_f32_16x16x32_bf16 v[12:15], v[144:147], v[208:211], v[12:15]
	v_mfma_f32_16x16x32_bf16 v[8:11], v[152:155], v[208:211], v[8:11]
	v_mfma_f32_16x16x32_bf16 v[60:63], v[148:151], v[188:191], v[60:63]
	v_mfma_f32_16x16x32_bf16 v[56:59], v[164:167], v[188:191], v[56:59]
	v_mfma_f32_16x16x32_bf16 v[44:47], v[148:151], v[196:199], v[44:47]
	v_mfma_f32_16x16x32_bf16 v[40:43], v[164:167], v[196:199], v[40:43]
	v_mfma_f32_16x16x32_bf16 v[28:31], v[148:151], v[204:207], v[28:31]
	v_mfma_f32_16x16x32_bf16 v[24:27], v[164:167], v[204:207], v[24:27]
	v_mfma_f32_16x16x32_bf16 v[12:15], v[148:151], v[212:215], v[12:15]
	v_mfma_f32_16x16x32_bf16 v[8:11], v[164:167], v[212:215], v[8:11]
	v_mfma_f32_16x16x32_bf16 v[52:55], v[168:171], v[184:187], v[52:55]
	v_mfma_f32_16x16x32_bf16 v[48:51], v[176:179], v[184:187], v[48:51]
	v_mfma_f32_16x16x32_bf16 v[36:39], v[168:171], v[192:195], v[36:39]
	v_mfma_f32_16x16x32_bf16 v[32:35], v[176:179], v[192:195], v[32:35]
	v_mfma_f32_16x16x32_bf16 v[20:23], v[168:171], v[200:203], v[20:23]
	v_mfma_f32_16x16x32_bf16 v[16:19], v[176:179], v[200:203], v[16:19]
	v_mfma_f32_16x16x32_bf16 v[4:7], v[168:171], v[208:211], v[4:7]
	v_mfma_f32_16x16x32_bf16 v[0:3], v[176:179], v[208:211], v[0:3]
	v_mfma_f32_16x16x32_bf16 v[52:55], v[172:175], v[188:191], v[52:55]
	v_mfma_f32_16x16x32_bf16 v[48:51], v[180:183], v[188:191], v[48:51]
	v_mfma_f32_16x16x32_bf16 v[36:39], v[172:175], v[196:199], v[36:39]
	v_mfma_f32_16x16x32_bf16 v[32:35], v[180:183], v[196:199], v[32:35]
	v_mfma_f32_16x16x32_bf16 v[20:23], v[172:175], v[204:207], v[20:23]
	v_mfma_f32_16x16x32_bf16 v[16:19], v[180:183], v[204:207], v[16:19]
	v_mfma_f32_16x16x32_bf16 v[4:7], v[172:175], v[212:215], v[4:7]
	v_mfma_f32_16x16x32_bf16 v[0:3], v[180:183], v[212:215], v[0:3]
	s_barrier
	s_add_i32 s55, s55, 2
	s_add_u32 s26, s26, 0x100
	s_addc_u32 s27, s27, 0
	s_add_u32 s53, s53, 0x100
	s_addc_u32 s54, s54, 0
	s_cmp_gt_u32 s55, 41
	s_cbranch_scc0 .LBB0_806
	s_setprio 0
	s_and_b64 vcc, exec, s[12:13]
	s_cbranch_vccz .LBB0_809
	s_barrier
